# pool-matrix weight conversion spread over 4x32 waves instead of the same 32 waves (layer-0 phase 0 and DeltaNet-scan converter half)
# speedup vs baseline: 1.0112x; 1.0058x over previous
; #define LAS __attribute__((address_space(3)))
; template <int MODE>
; DI void cvt_matrix(const float* W, int ldw, int nvalid, int K, int Npad, bf16_t* WT, LAS float* scr, int gw, int NGW, int lane) {
;     const int nblk = Npad / 32, nitems = (K / 64) * nblk;
;     for (int it = gw; it < nitems; it += NGW) {
;         const int kb = it / nblk, nb = it % nblk; int src0 = nb * 32;
;         if (MODE == 1) { const int pn = nb >> 3, wb = nb & 7; src0 = (wb < 4) ? pn * 128 + wb * 32 : FF + pn * 128 + (wb - 4) * 32; }
;         cvt_item(W, ldw, nvalid, src0, WT, K, nb * 32, kb * 64, scr, lane);
;     }
; }
; DI void convert_layer_weights(const Params& p, int layer, LAS float* scr, int gw, int NGW, int lane) {
;     cvt_matrix<1>(p.in[21] + (size_t)layer * D * NUP, NUP, NUP, D, NUP, (bf16_t*)(p.ws + w_up(layer)), scr, gw, NGW, lane);
;     cvt_matrix<0>(p.in[24] + (size_t)layer * FF * D, D, D, FF, D, (bf16_t*)(p.ws + w_dn(layer)), scr, gw, NGW, lane);
;     if (layer == 0 || layer == 3) {
;         for (int g = 0; g < 4; ++g) cvt_matrix<0>(p.in[11] + (size_t)((layer / 3) * 4 + g) * 65536, 256, 256, 256, 256, (bf16_t*)(p.ws + w_mix(layer)) + (size_t)g * 65536, scr, gw, NGW, lane);
.LBB0_784:
	s_lshl_b32 s8, s15, 5
	s_sub_i32 s8, s12, s8
	s_cmp_lt_u32 s8, 32
	s_cbranch_scc0 .LBB0_783
	s_lshl_b32 s8, s15, 16
	v_readlane_b32 s60, v254, 7
	s_lshl_b64 s[4:5], s[8:9], 2
	v_readlane_b32 s66, v254, 13
	v_readlane_b32 s67, v254, 14
	s_add_u32 s4, s66, s4
	s_addc_u32 s5, s67, s5
	s_add_u32 s4, s4, 0x100000
	s_addc_u32 s5, s5, 0
	s_lshl_b32 s8, s15, 17
	v_lshl_add_u64 v[2:3], v[0:1], 0, s[8:9]
	s_lshl_b32 s8, s15, 5
	s_sub_i32 s8, s12, s8
	v_readlane_b32 s61, v254, 8
	v_readlane_b32 s62, v254, 9
	v_readlane_b32 s63, v254, 10
	v_readlane_b32 s64, v254, 11
	v_readlane_b32 s65, v254, 12
	v_readlane_b32 s68, v254, 15
	v_readlane_b32 s69, v254, 16
	v_readlane_b32 s70, v254, 17
	v_readlane_b32 s71, v254, 18
	v_readlane_b32 s72, v254, 19
	v_readlane_b32 s73, v254, 20
	v_readlane_b32 s74, v254, 21
	v_readlane_b32 s75, v254, 22
	s_branch .LBB0_787

; #define LAS __attribute__((address_space(3)))
; template <int MODE>
; DI void cvt_matrix(const float* W, int ldw, int nvalid, int K, int Npad, bf16_t* WT, LAS float* scr, int gw, int NGW, int lane) {
;     const int nblk = Npad / 32, nitems = (K / 64) * nblk;
;     for (int it = gw; it < nitems; it += NGW) {
;         const int kb = it / nblk, nb = it % nblk; int src0 = nb * 32;
;         if (MODE == 1) { const int pn = nb >> 3, wb = nb & 7; src0 = (wb < 4) ? pn * 128 + wb * 32 : FF + pn * 128 + (wb - 4) * 32; }
;         cvt_item(W, ldw, nvalid, src0, WT, K, nb * 32, kb * 64, scr, lane);
;     }
; }
; DI void convert_layer_weights(const Params& p, int layer, LAS float* scr, int gw, int NGW, int lane) {
;     cvt_matrix<1>(p.in[21] + (size_t)layer * D * NUP, NUP, NUP, D, NUP, (bf16_t*)(p.ws + w_up(layer)), scr, gw, NGW, lane);
;     cvt_matrix<0>(p.in[24] + (size_t)layer * FF * D, D, D, FF, D, (bf16_t*)(p.ws + w_dn(layer)), scr, gw, NGW, lane);
;     if (layer == 0 || layer == 3) {
;         for (int g = 0; g < 4; ++g) cvt_matrix<0>(p.in[11] + (size_t)((layer / 3) * 4 + g) * 65536, 256, 256, 256, 256, (bf16_t*)(p.ws + w_mix(layer)) + (size_t)g * 65536, scr, gw, NGW, lane);
.LBB0_1561:
	s_lshl_b32 s8, s17, 5
	s_sub_i32 s8, s28, s8
	s_cmp_lt_u32 s8, 32
	s_cbranch_scc0 .LBB0_1560
	s_lshl_b32 s6, s17, 16
	s_add_i32 s8, s6, s18
	v_readlane_b32 s60, v254, 7
	s_lshl_b64 s[6:7], s[8:9], 2
	v_readlane_b32 s66, v254, 13
	v_readlane_b32 s67, v254, 14
	s_add_u32 s6, s66, s6
	s_addc_u32 s7, s67, s7
	s_lshl_b32 s8, s17, 17
	v_lshl_add_u64 v[2:3], v[0:1], 0, s[8:9]
	s_lshl_b32 s8, s17, 5
	s_sub_i32 s8, s28, s8
	v_readlane_b32 s61, v254, 8
	v_readlane_b32 s62, v254, 9
	v_readlane_b32 s63, v254, 10
	v_readlane_b32 s64, v254, 11
	v_readlane_b32 s65, v254, 12
	v_readlane_b32 s68, v254, 15
	v_readlane_b32 s69, v254, 16
	v_readlane_b32 s70, v254, 17
	v_readlane_b32 s71, v254, 18
	v_readlane_b32 s72, v254, 19
	v_readlane_b32 s73, v254, 20
	v_readlane_b32 s74, v254, 21
	v_readlane_b32 s75, v254, 22
	s_branch .LBB0_1564
